# v31 + sc1 (write-through) stores for the two SwiGLU GEMM outputs
# speedup vs baseline: 1.0024x; 1.0024x over previous
; __device__ __forceinline__ unsigned pkbf(float lo, float hi) { return pg8::cvt_pk_bf16(lo, hi); }
; __device__ __forceinline__ float fsigmoid(float x) { return __builtin_amdgcn_rcpf(1.f + __builtin_amdgcn_exp2f(-1.4426950408889634f * x)); }
;     __device__ __forceinline__ void operator()(AccRef acc, const Unit& u, int wr, int wc, int fr, int fq) const {
;         asm volatile("" : "+v"(fr), "+v"(fq));
;         const int row0 = u.pm * 256 + wr * 64 + fr, col0 = u.pn * 128 + wc * 32 + 8 * fq;
; #pragma unroll
;         for (int ai = 0; ai < 2; ++ai)
; #pragma unroll
;             for (int m = 0; m < 4; ++m) {
;                 bf16_t* rowp = O + (size_t)(row0 + ai * 128 + m * 16) * DFF + col0;
;                 float o[8];
; #pragma unroll
;                 for (int n = 0; n < 2; ++n)
; #pragma unroll
;                     for (int e = 0; e < 4; ++e) { const float g = acc[ai][0][m][n][e], up = acc[ai][1][m][n][e]; o[n * 4 + e] = g * fsigmoid(g) * up; }
;                 u32x4 w; w.x = pkbf(o[0], o[1]); w.y = pkbf(o[2], o[3]); w.z = pkbf(o[4], o[5]); w.w = pkbf(o[6], o[7]);
;                 *(u32x4*)rowp = w; __builtin_amdgcn_sched_barrier(0); asm volatile("" ::: "memory");
;             }
.LBB0_151:
	v_mul_f32_e32 v158, 0xbfb8aa3b, v120
	v_exp_f32_e32 v158, v158
	s_lshl_b32 s6, s68, 8
	v_mov_b32_e32 v146, v129
	v_mov_b32_e32 v147, v148
	v_add_f32_e32 v158, 1.0, v158
	v_rcp_f32_e32 v158, v158
	s_add_i32 s6, s6, s76
	v_mul_f32_e32 v120, v120, v158
	v_mul_f32_e32 v120, v124, v120
	v_mul_f32_e32 v124, 0xbfb8aa3b, v121
	v_exp_f32_e32 v124, v124
	v_add_u32_e32 v153, s6, v146
	s_lshl_b32 s6, s16, 7
	s_or_b32 s6, s6, s77
	v_add_f32_e32 v124, 1.0, v124
	v_rcp_f32_e32 v124, v124
	v_lshl_add_u32 v154, v147, 3, s6
	v_ashrrev_i32_e32 v155, 31, v154
	v_mov_b64_e32 v[146:147], s[22:23]
	v_mul_f32_e32 v121, v121, v124
	v_mul_f32_e32 v124, 0xbfb8aa3b, v122
	v_exp_f32_e32 v124, v124
	v_mad_i64_i32 v[156:157], s[6:7], v153, s89, v[146:147]
	v_mul_f32_e32 v121, v125, v121
	v_add_f32_e32 v124, 1.0, v124
	v_rcp_f32_e32 v124, v124
	s_nop 0
	v_mul_f32_e32 v122, v122, v124
	v_mul_f32_e32 v124, 0xbfb8aa3b, v123
	v_exp_f32_e32 v124, v124
	v_mul_f32_e32 v122, v126, v122
	v_add_f32_e32 v124, 1.0, v124
	v_rcp_f32_e32 v124, v124
	s_nop 0
	v_mul_f32_e32 v123, v123, v124
	v_mul_f32_e32 v124, 0xbfb8aa3b, v116
	v_exp_f32_e32 v124, v124
	v_mul_f32_e32 v123, v127, v123
	v_add_f32_e32 v124, 1.0, v124
	v_rcp_f32_e32 v124, v124
	s_nop 0
	v_mul_f32_e32 v116, v116, v124
	v_mul_f32_e32 v116, v112, v116
	v_mul_f32_e32 v112, 0xbfb8aa3b, v117
	v_exp_f32_e32 v112, v112
	s_nop 0
	v_add_f32_e32 v112, 1.0, v112
	v_rcp_f32_e32 v112, v112
	s_nop 0
	v_mul_f32_e32 v112, v117, v112
	v_mul_f32_e32 v117, v113, v112
	v_mul_f32_e32 v112, 0xbfb8aa3b, v118
	v_exp_f32_e32 v112, v112
	s_nop 0
	v_add_f32_e32 v112, 1.0, v112
	v_rcp_f32_e32 v112, v112
	s_nop 0
	v_mul_f32_e32 v112, v118, v112
	v_mul_f32_e32 v124, v114, v112
	v_mul_f32_e32 v112, 0xbfb8aa3b, v119
	v_exp_f32_e32 v112, v112
	v_cvt_pk_bf16_f32 v114, v120, v121
	s_nop 0
	v_add_f32_e32 v112, 1.0, v112
	v_rcp_f32_e32 v112, v112
	s_nop 0
	v_mul_f32_e32 v112, v119, v112
	v_mul_f32_e32 v125, v115, v112
	v_lshlrev_b64 v[112:113], 1, v[154:155]
	v_lshl_add_u64 v[118:119], v[156:157], 0, v[112:113]
	v_cvt_pk_bf16_f32 v115, v122, v123
	v_cvt_pk_bf16_f32 v116, v116, v117
	v_cvt_pk_bf16_f32 v117, v124, v125
	global_store_dwordx4 v[118:119], v[114:117], off sc1
	s_nop 1
	v_mul_f32_e32 v116, 0xbfb8aa3b, v108
	v_exp_f32_e32 v116, v116
	v_add_u32_e32 v114, 16, v153
	v_mad_i64_i32 v[114:115], s[6:7], v114, s89, v[146:147]
	v_add_f32_e32 v116, 1.0, v116
	v_rcp_f32_e32 v116, v116
	s_nop 0
	v_mul_f32_e32 v108, v108, v116
	v_mul_f32_e32 v104, v104, v108
	v_mul_f32_e32 v108, 0xbfb8aa3b, v109
	v_exp_f32_e32 v108, v108
	s_nop 0
	v_add_f32_e32 v108, 1.0, v108
	v_rcp_f32_e32 v108, v108
	s_nop 0
	v_mul_f32_e32 v108, v109, v108
	v_mul_f32_e32 v105, v105, v108
	v_mul_f32_e32 v108, 0xbfb8aa3b, v110
	v_exp_f32_e32 v108, v108
	s_nop 0
	v_add_f32_e32 v108, 1.0, v108
	v_rcp_f32_e32 v108, v108
	s_nop 0
	v_mul_f32_e32 v108, v110, v108
	v_mul_f32_e32 v106, v106, v108
	v_mul_f32_e32 v108, 0xbfb8aa3b, v111
	v_exp_f32_e32 v108, v108
	s_nop 0
	v_add_f32_e32 v108, 1.0, v108
	v_rcp_f32_e32 v108, v108
	s_nop 0
	v_mul_f32_e32 v108, v111, v108
	v_mul_f32_e32 v107, v107, v108
	v_mul_f32_e32 v108, 0xbfb8aa3b, v100
	v_exp_f32_e32 v108, v108
	s_nop 0
	v_add_f32_e32 v108, 1.0, v108
	v_rcp_f32_e32 v108, v108
	s_nop 0
	v_mul_f32_e32 v100, v100, v108
	v_mul_f32_e32 v108, v96, v100
	v_mul_f32_e32 v96, 0xbfb8aa3b, v101
	v_exp_f32_e32 v96, v96
	s_nop 0
	v_add_f32_e32 v96, 1.0, v96
	v_rcp_f32_e32 v96, v96
	s_nop 0
	v_mul_f32_e32 v96, v101, v96
	v_mul_f32_e32 v109, v97, v96
	v_mul_f32_e32 v96, 0xbfb8aa3b, v102
	v_exp_f32_e32 v96, v96
	v_lshl_add_u64 v[100:101], v[114:115], 0, v[112:113]
	v_add_f32_e32 v96, 1.0, v96
	v_rcp_f32_e32 v96, v96
	s_nop 0
	v_mul_f32_e32 v96, v102, v96
	v_mul_f32_e32 v102, v98, v96
	v_mul_f32_e32 v96, 0xbfb8aa3b, v103
	v_exp_f32_e32 v96, v96
	s_nop 0
	v_add_f32_e32 v96, 1.0, v96
	v_rcp_f32_e32 v96, v96
	s_nop 0
	v_mul_f32_e32 v96, v103, v96
	v_mul_f32_e32 v99, v99, v96
	v_cvt_pk_bf16_f32 v96, v104, v105
	v_cvt_pk_bf16_f32 v97, v106, v107
	v_cvt_pk_bf16_f32 v98, v108, v109
	v_cvt_pk_bf16_f32 v99, v102, v99
	global_store_dwordx4 v[100:101], v[96:99], off sc1
	s_nop 1
	v_mul_f32_e32 v98, 0xbfb8aa3b, v92
	v_exp_f32_e32 v98, v98
	v_add_u32_e32 v96, 32, v153
	v_mad_i64_i32 v[96:97], s[6:7], v96, s89, v[146:147]
	v_add_f32_e32 v98, 1.0, v98
	v_rcp_f32_e32 v98, v98
	s_nop 0
	v_mul_f32_e32 v92, v92, v98
	v_mul_f32_e32 v88, v88, v92
	v_mul_f32_e32 v92, 0xbfb8aa3b, v93
	v_exp_f32_e32 v92, v92
	s_nop 0
	v_add_f32_e32 v92, 1.0, v92
	v_rcp_f32_e32 v92, v92
	s_nop 0
	v_mul_f32_e32 v92, v93, v92
	v_mul_f32_e32 v89, v89, v92
	v_mul_f32_e32 v92, 0xbfb8aa3b, v94
	v_exp_f32_e32 v92, v92
	s_nop 0
	v_add_f32_e32 v92, 1.0, v92
	v_rcp_f32_e32 v92, v92
	s_nop 0
	v_mul_f32_e32 v92, v94, v92
	v_mul_f32_e32 v90, v90, v92
	v_mul_f32_e32 v92, 0xbfb8aa3b, v95
	v_exp_f32_e32 v92, v92
	s_nop 0
	v_add_f32_e32 v92, 1.0, v92
	v_rcp_f32_e32 v92, v92
	s_nop 0
	v_mul_f32_e32 v92, v95, v92
	v_mul_f32_e32 v91, v91, v92
	v_mul_f32_e32 v92, 0xbfb8aa3b, v84
	v_exp_f32_e32 v92, v92
	s_nop 0
	v_add_f32_e32 v92, 1.0, v92
	v_rcp_f32_e32 v92, v92
	s_nop 0
	v_mul_f32_e32 v84, v84, v92
	v_mul_f32_e32 v92, v80, v84
	v_mul_f32_e32 v80, 0xbfb8aa3b, v85
	v_exp_f32_e32 v80, v80
	s_nop 0
	v_add_f32_e32 v80, 1.0, v80
	v_rcp_f32_e32 v80, v80
	s_nop 0
	v_mul_f32_e32 v80, v85, v80
	v_mul_f32_e32 v93, v81, v80
	v_mul_f32_e32 v80, 0xbfb8aa3b, v86
	v_exp_f32_e32 v80, v80
	v_lshl_add_u64 v[84:85], v[96:97], 0, v[112:113]
	v_add_f32_e32 v80, 1.0, v80
	v_rcp_f32_e32 v80, v80
	s_nop 0
	v_mul_f32_e32 v80, v86, v80
	v_mul_f32_e32 v86, v82, v80
	v_mul_f32_e32 v80, 0xbfb8aa3b, v87
	v_exp_f32_e32 v80, v80
	s_nop 0
; __device__ __forceinline__ unsigned pkbf(float lo, float hi) { return pg8::cvt_pk_bf16(lo, hi); }
; __device__ __forceinline__ float fsigmoid(float x) { return __builtin_amdgcn_rcpf(1.f + __builtin_amdgcn_exp2f(-1.4426950408889634f * x)); }
;     __device__ __forceinline__ void operator()(AccRef acc, const Unit& u, int wr, int wc, int fr, int fq) const {
;         asm volatile("" : "+v"(fr), "+v"(fq));
;         const int row0 = u.pm * 256 + wr * 64 + fr, col0 = u.pn * 128 + wc * 32 + 8 * fq;
; #pragma unroll
;         for (int ai = 0; ai < 2; ++ai)
; #pragma unroll
;             for (int m = 0; m < 4; ++m) {
;                 bf16_t* rowp = O + (size_t)(row0 + ai * 128 + m * 16) * DFF + col0;
;                 float o[8];
; #pragma unroll
;                 for (int n = 0; n < 2; ++n)
; #pragma unroll
;                     for (int e = 0; e < 4; ++e) { const float g = acc[ai][0][m][n][e], up = acc[ai][1][m][n][e]; o[n * 4 + e] = g * fsigmoid(g) * up; }
;                 u32x4 w; w.x = pkbf(o[0], o[1]); w.y = pkbf(o[2], o[3]); w.z = pkbf(o[4], o[5]); w.w = pkbf(o[6], o[7]);
;                 *(u32x4*)rowp = w; __builtin_amdgcn_sched_barrier(0); asm volatile("" ::: "memory");
;             }
	v_add_f32_e32 v80, 1.0, v80
	v_rcp_f32_e32 v80, v80
	s_nop 0
	v_mul_f32_e32 v80, v87, v80
	v_mul_f32_e32 v83, v83, v80
	v_cvt_pk_bf16_f32 v80, v88, v89
	v_cvt_pk_bf16_f32 v81, v90, v91
	v_cvt_pk_bf16_f32 v82, v92, v93
	v_cvt_pk_bf16_f32 v83, v86, v83
	global_store_dwordx4 v[84:85], v[80:83], off sc1
	s_nop 1
	v_mul_f32_e32 v82, 0xbfb8aa3b, v76
	v_exp_f32_e32 v82, v82
	v_add_u32_e32 v80, 48, v153
	v_mad_i64_i32 v[80:81], s[6:7], v80, s89, v[146:147]
	v_add_f32_e32 v82, 1.0, v82
	v_rcp_f32_e32 v82, v82
	s_nop 0
	v_mul_f32_e32 v76, v76, v82
	v_mul_f32_e32 v72, v72, v76
	v_mul_f32_e32 v76, 0xbfb8aa3b, v77
	v_exp_f32_e32 v76, v76
	s_nop 0
	v_add_f32_e32 v76, 1.0, v76
	v_rcp_f32_e32 v76, v76
	s_nop 0
	v_mul_f32_e32 v76, v77, v76
	v_mul_f32_e32 v73, v73, v76
	v_mul_f32_e32 v76, 0xbfb8aa3b, v78
	v_exp_f32_e32 v76, v76
	s_nop 0
	v_add_f32_e32 v76, 1.0, v76
	v_rcp_f32_e32 v76, v76
	s_nop 0
	v_mul_f32_e32 v76, v78, v76
	v_mul_f32_e32 v74, v74, v76
	v_mul_f32_e32 v76, 0xbfb8aa3b, v79
	v_exp_f32_e32 v76, v76
	s_nop 0
	v_add_f32_e32 v76, 1.0, v76
	v_rcp_f32_e32 v76, v76
	s_nop 0
	v_mul_f32_e32 v76, v79, v76
	v_mul_f32_e32 v75, v75, v76
	v_mul_f32_e32 v76, 0xbfb8aa3b, v68
	v_exp_f32_e32 v76, v76
	s_nop 0
	v_add_f32_e32 v76, 1.0, v76
	v_rcp_f32_e32 v76, v76
	s_nop 0
	v_mul_f32_e32 v68, v68, v76
	v_mul_f32_e32 v76, v64, v68
	v_mul_f32_e32 v64, 0xbfb8aa3b, v69
	v_exp_f32_e32 v64, v64
	s_nop 0
	v_add_f32_e32 v64, 1.0, v64
	v_rcp_f32_e32 v64, v64
	s_nop 0
	v_mul_f32_e32 v64, v69, v64
	v_mul_f32_e32 v77, v65, v64
	v_mul_f32_e32 v64, 0xbfb8aa3b, v70
	v_exp_f32_e32 v64, v64
	v_lshl_add_u64 v[68:69], v[80:81], 0, v[112:113]
	v_add_f32_e32 v64, 1.0, v64
	v_rcp_f32_e32 v64, v64
	s_nop 0
	v_mul_f32_e32 v64, v70, v64
	v_mul_f32_e32 v70, v66, v64
	v_mul_f32_e32 v64, 0xbfb8aa3b, v71
	v_exp_f32_e32 v64, v64
	s_nop 0
	v_add_f32_e32 v64, 1.0, v64
	v_rcp_f32_e32 v64, v64
	s_nop 0
	v_mul_f32_e32 v64, v71, v64
	v_mul_f32_e32 v67, v67, v64
	v_cvt_pk_bf16_f32 v64, v72, v73
	v_cvt_pk_bf16_f32 v65, v74, v75
	v_cvt_pk_bf16_f32 v66, v76, v77
	v_cvt_pk_bf16_f32 v67, v70, v67
	global_store_dwordx4 v[68:69], v[64:67], off sc1
	s_nop 1
	v_mul_f32_e32 v66, 0xbfb8aa3b, v60
	v_exp_f32_e32 v66, v66
	v_add_u32_e32 v64, 0x80, v153
	v_mad_i64_i32 v[64:65], s[6:7], v64, s89, v[146:147]
	v_add_f32_e32 v66, 1.0, v66
	v_rcp_f32_e32 v66, v66
	s_nop 0
	v_mul_f32_e32 v60, v60, v66
	v_mul_f32_e32 v56, v56, v60
	v_mul_f32_e32 v60, 0xbfb8aa3b, v61
	v_exp_f32_e32 v60, v60
	s_nop 0
	v_add_f32_e32 v60, 1.0, v60
	v_rcp_f32_e32 v60, v60
	s_nop 0
	v_mul_f32_e32 v60, v61, v60
	v_mul_f32_e32 v57, v57, v60
	v_mul_f32_e32 v60, 0xbfb8aa3b, v62
	v_exp_f32_e32 v60, v60
	s_nop 0
	v_add_f32_e32 v60, 1.0, v60
	v_rcp_f32_e32 v60, v60
	s_nop 0
	v_mul_f32_e32 v60, v62, v60
	v_mul_f32_e32 v58, v58, v60
	v_mul_f32_e32 v60, 0xbfb8aa3b, v63
	v_exp_f32_e32 v60, v60
	s_nop 0
	v_add_f32_e32 v60, 1.0, v60
	v_rcp_f32_e32 v60, v60
	s_nop 0
	v_mul_f32_e32 v60, v63, v60
	v_mul_f32_e32 v59, v59, v60
	v_mul_f32_e32 v60, 0xbfb8aa3b, v52
	v_exp_f32_e32 v60, v60
	s_nop 0
	v_add_f32_e32 v60, 1.0, v60
	v_rcp_f32_e32 v60, v60
	s_nop 0
	v_mul_f32_e32 v52, v52, v60
	v_mul_f32_e32 v60, v48, v52
	v_mul_f32_e32 v48, 0xbfb8aa3b, v53
	v_exp_f32_e32 v48, v48
	s_nop 0
	v_add_f32_e32 v48, 1.0, v48
	v_rcp_f32_e32 v48, v48
	s_nop 0
	v_mul_f32_e32 v48, v53, v48
	v_mul_f32_e32 v61, v49, v48
	v_mul_f32_e32 v48, 0xbfb8aa3b, v54
	v_exp_f32_e32 v48, v48
	v_lshl_add_u64 v[52:53], v[64:65], 0, v[112:113]
	v_add_f32_e32 v48, 1.0, v48
	v_rcp_f32_e32 v48, v48
	s_nop 0
	v_mul_f32_e32 v48, v54, v48
	v_mul_f32_e32 v54, v50, v48
	v_mul_f32_e32 v48, 0xbfb8aa3b, v55
	v_exp_f32_e32 v48, v48
	s_nop 0
	v_add_f32_e32 v48, 1.0, v48
	v_rcp_f32_e32 v48, v48
	s_nop 0
	v_mul_f32_e32 v48, v55, v48
	v_mul_f32_e32 v51, v51, v48
	v_cvt_pk_bf16_f32 v48, v56, v57
	v_cvt_pk_bf16_f32 v49, v58, v59
	v_cvt_pk_bf16_f32 v50, v60, v61
	v_cvt_pk_bf16_f32 v51, v54, v51
	global_store_dwordx4 v[52:53], v[48:51], off sc1
	s_nop 1
	v_mul_f32_e32 v50, 0xbfb8aa3b, v44
	v_exp_f32_e32 v50, v50
	v_add_u32_e32 v48, 0x90, v153
	v_mad_i64_i32 v[48:49], s[6:7], v48, s89, v[146:147]
	v_add_f32_e32 v50, 1.0, v50
	v_rcp_f32_e32 v50, v50
	s_nop 0
	v_mul_f32_e32 v44, v44, v50
	v_mul_f32_e32 v40, v40, v44
	v_mul_f32_e32 v44, 0xbfb8aa3b, v45
	v_exp_f32_e32 v44, v44
	s_nop 0
	v_add_f32_e32 v44, 1.0, v44
	v_rcp_f32_e32 v44, v44
	s_nop 0
	v_mul_f32_e32 v44, v45, v44
	v_mul_f32_e32 v41, v41, v44
	v_mul_f32_e32 v44, 0xbfb8aa3b, v46
	v_exp_f32_e32 v44, v44
	s_nop 0
	v_add_f32_e32 v44, 1.0, v44
	v_rcp_f32_e32 v44, v44
	s_nop 0
	v_mul_f32_e32 v44, v46, v44
	v_mul_f32_e32 v42, v42, v44
	v_mul_f32_e32 v44, 0xbfb8aa3b, v47
	v_exp_f32_e32 v44, v44
	s_nop 0
	v_add_f32_e32 v44, 1.0, v44
	v_rcp_f32_e32 v44, v44
	s_nop 0
	v_mul_f32_e32 v44, v47, v44
; #define PG8_BAR __builtin_amdgcn_s_barrier()
; __device__ __forceinline__ unsigned pkbf(float lo, float hi) { return pg8::cvt_pk_bf16(lo, hi); }
; __device__ __forceinline__ float fsigmoid(float x) { return __builtin_amdgcn_rcpf(1.f + __builtin_amdgcn_exp2f(-1.4426950408889634f * x)); }
; template <class Epi, class Sched, bool ALIGN_EPI = false, bool SP2 = false>
; __device__ __forceinline__ void gemm_phase(PG8_LAS unsigned char* lds, const Gemm g, const Sched& S, const Epi& E) {
;     ...
;         if constexpr (ALIGN_EPI) { if (wr == 0) PG8_BAR; }
;         if constexpr (!Epi::AFTER_DRAIN) { E(acc, cur, wr, wc, fr, fq); S.done(cur); }
;         if (!has_next) break;
; #pragma unroll
;         for (int a = 0; a < 2; ++a)
; #pragma unroll
;             for (int b = 0; b < 2; ++b)
; #pragma unroll
;                 for (int m = 0; m < 4; ++m)
; #pragma unroll
;                     for (int n = 0; n < 2; ++n) acc[a][b][m][n] = (f32x4){0.f, 0.f, 0.f, 0.f};
;         cur = nxt; cA = nA; cB = nB; ++ui;
;         if constexpr (ALIGN_EPI) { if (wr == 1) PG8_BAR; }
;     }
;     __device__ __forceinline__ void operator()(AccRef acc, const Unit& u, int wr, int wc, int fr, int fq) const {
;         asm volatile("" : "+v"(fr), "+v"(fq));
;         const int row0 = u.pm * 256 + wr * 64 + fr, col0 = u.pn * 128 + wc * 32 + 8 * fq;
; #pragma unroll
;         for (int ai = 0; ai < 2; ++ai)
; #pragma unroll
;             for (int m = 0; m < 4; ++m) {
;                 bf16_t* rowp = O + (size_t)(row0 + ai * 128 + m * 16) * DFF + col0;
;                 float o[8];
; #pragma unroll
;                 for (int n = 0; n < 2; ++n)
; #pragma unroll
;                     for (int e = 0; e < 4; ++e) { const float g = acc[ai][0][m][n][e], up = acc[ai][1][m][n][e]; o[n * 4 + e] = g * fsigmoid(g) * up; }
;                 u32x4 w; w.x = pkbf(o[0], o[1]); w.y = pkbf(o[2], o[3]); w.z = pkbf(o[4], o[5]); w.w = pkbf(o[6], o[7]);
;                 *(u32x4*)rowp = w; __builtin_amdgcn_sched_barrier(0); asm volatile("" ::: "memory");
;             }
;     }
	v_mul_f32_e32 v43, v43, v44
	v_mul_f32_e32 v44, 0xbfb8aa3b, v36
	v_exp_f32_e32 v44, v44
	s_nop 0
	v_add_f32_e32 v44, 1.0, v44
	v_rcp_f32_e32 v44, v44
	s_nop 0
	v_mul_f32_e32 v36, v36, v44
	v_mul_f32_e32 v44, v32, v36
	v_mul_f32_e32 v32, 0xbfb8aa3b, v37
	v_exp_f32_e32 v32, v32
	s_nop 0
	v_add_f32_e32 v32, 1.0, v32
	v_rcp_f32_e32 v32, v32
	s_nop 0
	v_mul_f32_e32 v32, v37, v32
	v_mul_f32_e32 v45, v33, v32
	v_mul_f32_e32 v32, 0xbfb8aa3b, v38
	v_exp_f32_e32 v32, v32
	v_lshl_add_u64 v[36:37], v[48:49], 0, v[112:113]
	v_add_f32_e32 v32, 1.0, v32
	v_rcp_f32_e32 v32, v32
	s_nop 0
	v_mul_f32_e32 v32, v38, v32
	v_mul_f32_e32 v38, v34, v32
	v_mul_f32_e32 v32, 0xbfb8aa3b, v39
	v_exp_f32_e32 v32, v32
	s_nop 0
	v_add_f32_e32 v32, 1.0, v32
	v_rcp_f32_e32 v32, v32
	s_nop 0
	v_mul_f32_e32 v32, v39, v32
	v_mul_f32_e32 v35, v35, v32
	v_cvt_pk_bf16_f32 v32, v40, v41
	v_cvt_pk_bf16_f32 v33, v42, v43
	v_cvt_pk_bf16_f32 v34, v44, v45
	v_cvt_pk_bf16_f32 v35, v38, v35
	global_store_dwordx4 v[36:37], v[32:35], off sc1
	s_nop 1
	v_mul_f32_e32 v34, 0xbfb8aa3b, v28
	v_exp_f32_e32 v34, v34
	v_add_u32_e32 v32, 0xa0, v153
	v_mad_i64_i32 v[32:33], s[6:7], v32, s89, v[146:147]
	v_add_f32_e32 v34, 1.0, v34
	v_rcp_f32_e32 v34, v34
	s_nop 0
	v_mul_f32_e32 v28, v28, v34
	v_mul_f32_e32 v24, v24, v28
	v_mul_f32_e32 v28, 0xbfb8aa3b, v29
	v_exp_f32_e32 v28, v28
	s_nop 0
	v_add_f32_e32 v28, 1.0, v28
	v_rcp_f32_e32 v28, v28
	s_nop 0
	v_mul_f32_e32 v28, v29, v28
	v_mul_f32_e32 v25, v25, v28
	v_mul_f32_e32 v28, 0xbfb8aa3b, v30
	v_exp_f32_e32 v28, v28
	s_nop 0
	v_add_f32_e32 v28, 1.0, v28
	v_rcp_f32_e32 v28, v28
	s_nop 0
	v_mul_f32_e32 v28, v30, v28
	v_mul_f32_e32 v26, v26, v28
	v_mul_f32_e32 v28, 0xbfb8aa3b, v31
	v_exp_f32_e32 v28, v28
	s_nop 0
	v_add_f32_e32 v28, 1.0, v28
	v_rcp_f32_e32 v28, v28
	s_nop 0
	v_mul_f32_e32 v28, v31, v28
	v_mul_f32_e32 v27, v27, v28
	v_mul_f32_e32 v28, 0xbfb8aa3b, v20
	v_exp_f32_e32 v28, v28
	s_nop 0
	v_add_f32_e32 v28, 1.0, v28
	v_rcp_f32_e32 v28, v28
	s_nop 0
	v_mul_f32_e32 v20, v20, v28
	v_mul_f32_e32 v28, v16, v20
	v_mul_f32_e32 v16, 0xbfb8aa3b, v21
	v_exp_f32_e32 v16, v16
	s_nop 0
	v_add_f32_e32 v16, 1.0, v16
	v_rcp_f32_e32 v16, v16
	s_nop 0
	v_mul_f32_e32 v16, v21, v16
	v_mul_f32_e32 v29, v17, v16
	v_mul_f32_e32 v16, 0xbfb8aa3b, v22
	v_exp_f32_e32 v16, v16
	v_lshl_add_u64 v[20:21], v[32:33], 0, v[112:113]
	v_add_f32_e32 v16, 1.0, v16
	v_rcp_f32_e32 v16, v16
	s_nop 0
	v_mul_f32_e32 v16, v22, v16
	v_mul_f32_e32 v22, v18, v16
	v_mul_f32_e32 v16, 0xbfb8aa3b, v23
	v_exp_f32_e32 v16, v16
	s_nop 0
	v_add_f32_e32 v16, 1.0, v16
	v_rcp_f32_e32 v16, v16
	s_nop 0
	v_mul_f32_e32 v16, v23, v16
	v_mul_f32_e32 v19, v19, v16
	v_cvt_pk_bf16_f32 v16, v24, v25
	v_cvt_pk_bf16_f32 v17, v26, v27
	v_cvt_pk_bf16_f32 v18, v28, v29
	v_cvt_pk_bf16_f32 v19, v22, v19
	global_store_dwordx4 v[20:21], v[16:19], off sc1
	s_nop 1
	v_mul_f32_e32 v18, 0xbfb8aa3b, v12
	v_exp_f32_e32 v18, v18
	v_add_u32_e32 v16, 0xb0, v153
	v_mad_i64_i32 v[16:17], s[6:7], v16, s89, v[146:147]
	v_add_f32_e32 v18, 1.0, v18
	v_rcp_f32_e32 v18, v18
	s_nop 0
	v_mul_f32_e32 v12, v12, v18
	v_mul_f32_e32 v8, v8, v12
	v_mul_f32_e32 v12, 0xbfb8aa3b, v13
	v_exp_f32_e32 v12, v12
	s_nop 0
	v_add_f32_e32 v12, 1.0, v12
	v_rcp_f32_e32 v12, v12
	s_nop 0
	v_mul_f32_e32 v12, v13, v12
	v_mul_f32_e32 v9, v9, v12
	v_mul_f32_e32 v12, 0xbfb8aa3b, v14
	v_exp_f32_e32 v12, v12
	s_nop 0
	v_add_f32_e32 v12, 1.0, v12
	v_rcp_f32_e32 v12, v12
	s_nop 0
	v_mul_f32_e32 v12, v14, v12
	v_mul_f32_e32 v10, v10, v12
	v_mul_f32_e32 v12, 0xbfb8aa3b, v15
	v_exp_f32_e32 v12, v12
	s_nop 0
	v_add_f32_e32 v12, 1.0, v12
	v_rcp_f32_e32 v12, v12
	s_nop 0
	v_mul_f32_e32 v12, v15, v12
	v_mul_f32_e32 v11, v11, v12
	v_mul_f32_e32 v12, 0xbfb8aa3b, v4
	v_exp_f32_e32 v12, v12
	s_nop 0
	v_add_f32_e32 v12, 1.0, v12
	v_rcp_f32_e32 v12, v12
	s_nop 0
	v_mul_f32_e32 v4, v4, v12
	v_mul_f32_e32 v12, v0, v4
	v_mul_f32_e32 v0, 0xbfb8aa3b, v5
	v_exp_f32_e32 v0, v0
	s_nop 0
	v_add_f32_e32 v0, 1.0, v0
	v_rcp_f32_e32 v0, v0
	s_nop 0
	v_mul_f32_e32 v0, v5, v0
	v_mul_f32_e32 v13, v1, v0
	v_mul_f32_e32 v0, 0xbfb8aa3b, v6
	v_exp_f32_e32 v0, v0
	v_lshl_add_u64 v[4:5], v[16:17], 0, v[112:113]
	v_add_f32_e32 v0, 1.0, v0
	v_rcp_f32_e32 v0, v0
	s_nop 0
	v_mul_f32_e32 v0, v6, v0
	v_mul_f32_e32 v6, v2, v0
	v_mul_f32_e32 v0, 0xbfb8aa3b, v7
	v_exp_f32_e32 v0, v0
	s_nop 0
	v_add_f32_e32 v0, 1.0, v0
	v_rcp_f32_e32 v0, v0
	s_nop 0
	v_mul_f32_e32 v0, v7, v0
	v_mul_f32_e32 v3, v3, v0
	v_cvt_pk_bf16_f32 v0, v8, v9
	v_cvt_pk_bf16_f32 v1, v10, v11
	v_cvt_pk_bf16_f32 v2, v12, v13
	v_cvt_pk_bf16_f32 v3, v6, v3
	global_store_dwordx4 v[4:5], v[0:3], off sc1
	s_and_b64 vcc, exec, s[4:5]
	s_mov_b64 s[4:5], -1
	s_cbranch_vccnz .LBB0_141
	s_andn2_b64 vcc, exec, s[30:31]
	s_cbranch_vccnz .LBB0_140
	s_barrier
	s_branch .LBB0_140

; __device__ __forceinline__ unsigned pkbf(float lo, float hi) { return pg8::cvt_pk_bf16(lo, hi); }
; __device__ __forceinline__ float fsigmoid(float x) { return __builtin_amdgcn_rcpf(1.f + __builtin_amdgcn_exp2f(-1.4426950408889634f * x)); }
;     __device__ __forceinline__ void operator()(AccRef acc, const Unit& u, int wr, int wc, int fr, int fq) const {
;         asm volatile("" : "+v"(fr), "+v"(fq));
;         const int row0 = u.pm * 256 + wr * 64 + fr, col0 = u.pn * 128 + wc * 32 + 8 * fq;
; #pragma unroll
;         for (int ai = 0; ai < 2; ++ai)
; #pragma unroll
;             for (int m = 0; m < 4; ++m) {
;                 bf16_t* rowp = O + (size_t)(row0 + ai * 128 + m * 16) * DFF + col0;
;                 float o[8];
; #pragma unroll
;                 for (int n = 0; n < 2; ++n)
; #pragma unroll
;                     for (int e = 0; e < 4; ++e) { const float g = acc[ai][0][m][n][e], up = acc[ai][1][m][n][e]; o[n * 4 + e] = g * fsigmoid(g) * up; }
;                 u32x4 w; w.x = pkbf(o[0], o[1]); w.y = pkbf(o[2], o[3]); w.z = pkbf(o[4], o[5]); w.w = pkbf(o[6], o[7]);
;                 *(u32x4*)rowp = w; __builtin_amdgcn_sched_barrier(0); asm volatile("" ::: "memory");
;             }
.LBB0_1370:
	v_mov_b32_e32 v146, v129
	v_mov_b32_e32 v147, v148
	s_lshl_b32 s4, s36, 8
	s_add_i32 s4, s4, s52
	v_add_u32_e32 v153, s4, v146
	v_mul_f32_e32 v146, 0xbfb8aa3b, v124
	v_exp_f32_e32 v156, v146
	v_mul_f32_e32 v146, 0xbfb8aa3b, v125
	v_exp_f32_e32 v157, v146
	s_lshl_b32 s4, s59, 7
	v_add_f32_e32 v156, 1.0, v156
	v_rcp_f32_e32 v158, v156
	v_add_f32_e32 v156, 1.0, v157
	v_rcp_f32_e32 v159, v156
	s_or_b32 s4, s4, s53
	v_mul_f32_e32 v124, v124, v158
	v_mul_f32_e32 v120, v120, v124
	v_mul_f32_e32 v124, v125, v159
	v_mul_f32_e32 v125, 0xbfb8aa3b, v126
	v_exp_f32_e32 v125, v125
	v_mul_f32_e32 v158, 0xbfb8aa3b, v127
	v_exp_f32_e32 v158, v158
	v_mul_f32_e32 v121, v121, v124
	v_add_f32_e32 v124, 1.0, v125
	v_rcp_f32_e32 v124, v124
	v_add_f32_e32 v125, 1.0, v158
	v_mul_f32_e32 v158, 0xbfb8aa3b, v116
	v_rcp_f32_e32 v125, v125
	v_exp_f32_e32 v158, v158
	v_mul_f32_e32 v124, v126, v124
	v_mul_f32_e32 v122, v122, v124
	v_mul_f32_e32 v124, v127, v125
	v_add_f32_e32 v125, 1.0, v158
	v_rcp_f32_e32 v125, v125
	v_mul_f32_e32 v126, 0xbfb8aa3b, v117
	v_exp_f32_e32 v126, v126
	v_mul_f32_e32 v123, v123, v124
	v_mul_f32_e32 v116, v116, v125
	v_mul_f32_e32 v116, v112, v116
	v_add_f32_e32 v112, 1.0, v126
	v_mul_f32_e32 v124, 0xbfb8aa3b, v118
	v_rcp_f32_e32 v112, v112
	v_exp_f32_e32 v124, v124
	v_mul_f32_e32 v125, 0xbfb8aa3b, v119
	v_exp_f32_e32 v125, v125
	v_mul_f32_e32 v112, v117, v112
	v_add_f32_e32 v117, 1.0, v124
	v_rcp_f32_e32 v117, v117
	v_add_f32_e32 v124, 1.0, v125
	v_rcp_f32_e32 v124, v124
	v_lshl_add_u32 v154, v147, 3, s4
	v_mul_f32_e32 v125, v113, v112
	v_mul_f32_e32 v112, v118, v117
	v_ashrrev_i32_e32 v155, 31, v154
	v_mov_b64_e32 v[146:147], s[22:23]
	v_mul_f32_e32 v117, v114, v112
	v_mul_f32_e32 v112, v119, v124
	v_mad_i64_i32 v[156:157], s[4:5], v153, s57, v[146:147]
	v_mul_f32_e32 v124, v115, v112
	v_lshlrev_b64 v[112:113], 1, v[154:155]
	v_lshl_add_u64 v[118:119], v[156:157], 0, v[112:113]
	v_cvt_pk_bf16_f32 v114, v120, v121
	v_cvt_pk_bf16_f32 v115, v122, v123
	v_cvt_pk_bf16_f32 v116, v116, v125
	v_cvt_pk_bf16_f32 v117, v117, v124
	global_store_dwordx4 v[118:119], v[114:117], off sc1
	s_nop 1
	v_mul_f32_e32 v114, 0xbfb8aa3b, v108
	v_exp_f32_e32 v114, v114
	v_mul_f32_e32 v115, 0xbfb8aa3b, v109
	v_exp_f32_e32 v115, v115
	v_add_u32_e32 v116, 16, v153
	v_add_f32_e32 v114, 1.0, v114
	v_rcp_f32_e32 v117, v114
	v_add_f32_e32 v114, 1.0, v115
	v_rcp_f32_e32 v118, v114
	v_mad_i64_i32 v[114:115], s[4:5], v116, s57, v[146:147]
	v_mul_f32_e32 v108, v108, v117
	v_mul_f32_e32 v104, v104, v108
	v_mul_f32_e32 v108, v109, v118
	v_mul_f32_e32 v109, 0xbfb8aa3b, v110
	v_exp_f32_e32 v109, v109
	v_mul_f32_e32 v116, 0xbfb8aa3b, v111
	v_exp_f32_e32 v116, v116
	v_mul_f32_e32 v105, v105, v108
	v_add_f32_e32 v108, 1.0, v109
	v_rcp_f32_e32 v108, v108
	v_add_f32_e32 v109, 1.0, v116
	v_mul_f32_e32 v116, 0xbfb8aa3b, v100
	v_rcp_f32_e32 v109, v109
	v_exp_f32_e32 v116, v116
	v_mul_f32_e32 v108, v110, v108
	v_mul_f32_e32 v106, v106, v108
	v_mul_f32_e32 v108, v111, v109
	v_add_f32_e32 v109, 1.0, v116
	v_rcp_f32_e32 v109, v109
	v_mul_f32_e32 v110, 0xbfb8aa3b, v101
	v_exp_f32_e32 v110, v110
	v_mul_f32_e32 v107, v107, v108
	v_mul_f32_e32 v100, v100, v109
	v_mul_f32_e32 v108, v96, v100
	v_mul_f32_e32 v100, 0xbfb8aa3b, v102
	v_add_f32_e32 v96, 1.0, v110
	v_exp_f32_e32 v100, v100
	v_mul_f32_e32 v109, 0xbfb8aa3b, v103
	v_rcp_f32_e32 v96, v96
	v_exp_f32_e32 v109, v109
	v_add_f32_e32 v100, 1.0, v100
	v_rcp_f32_e32 v100, v100
	v_mul_f32_e32 v96, v101, v96
	v_add_f32_e32 v101, 1.0, v109
	v_rcp_f32_e32 v101, v101
	v_mul_f32_e32 v109, v97, v96
	v_mul_f32_e32 v96, v102, v100
	v_mul_f32_e32 v102, v98, v96
	v_mul_f32_e32 v96, v103, v101
	v_mul_f32_e32 v99, v99, v96
	v_lshl_add_u64 v[100:101], v[114:115], 0, v[112:113]
	v_cvt_pk_bf16_f32 v96, v104, v105
	v_cvt_pk_bf16_f32 v97, v106, v107
	v_cvt_pk_bf16_f32 v98, v108, v109
	v_cvt_pk_bf16_f32 v99, v102, v99
	global_store_dwordx4 v[100:101], v[96:99], off sc1
	s_nop 1
	v_mul_f32_e32 v96, 0xbfb8aa3b, v92
	v_exp_f32_e32 v96, v96
	v_mul_f32_e32 v97, 0xbfb8aa3b, v93
	v_exp_f32_e32 v97, v97
	v_add_u32_e32 v98, 32, v153
	v_add_f32_e32 v96, 1.0, v96
	v_rcp_f32_e32 v99, v96
	v_add_f32_e32 v96, 1.0, v97
	v_rcp_f32_e32 v100, v96
	v_mad_i64_i32 v[96:97], s[4:5], v98, s57, v[146:147]
	v_mul_f32_e32 v92, v92, v99
	v_mul_f32_e32 v88, v88, v92
	v_mul_f32_e32 v92, v93, v100
	v_mul_f32_e32 v93, 0xbfb8aa3b, v94
	v_exp_f32_e32 v93, v93
	v_mul_f32_e32 v98, 0xbfb8aa3b, v95
	v_exp_f32_e32 v98, v98
	v_mul_f32_e32 v89, v89, v92
	v_add_f32_e32 v92, 1.0, v93
	v_rcp_f32_e32 v92, v92
	v_add_f32_e32 v93, 1.0, v98
	v_mul_f32_e32 v98, 0xbfb8aa3b, v84
	v_rcp_f32_e32 v93, v93
	v_exp_f32_e32 v98, v98
	v_mul_f32_e32 v92, v94, v92
	v_mul_f32_e32 v90, v90, v92
	v_mul_f32_e32 v92, v95, v93
	v_add_f32_e32 v93, 1.0, v98
	v_rcp_f32_e32 v93, v93
	v_mul_f32_e32 v94, 0xbfb8aa3b, v85
	v_exp_f32_e32 v94, v94
	v_mul_f32_e32 v91, v91, v92
	v_mul_f32_e32 v84, v84, v93
	v_mul_f32_e32 v92, v80, v84
	v_mul_f32_e32 v84, 0xbfb8aa3b, v86
	v_add_f32_e32 v80, 1.0, v94
	v_exp_f32_e32 v84, v84
	v_mul_f32_e32 v93, 0xbfb8aa3b, v87
	v_rcp_f32_e32 v80, v80
	v_exp_f32_e32 v93, v93
	v_add_f32_e32 v84, 1.0, v84
	v_rcp_f32_e32 v84, v84
	v_mul_f32_e32 v80, v85, v80
	v_add_f32_e32 v85, 1.0, v93
	v_rcp_f32_e32 v85, v85
	v_mul_f32_e32 v93, v81, v80
	v_mul_f32_e32 v80, v86, v84
	v_mul_f32_e32 v86, v82, v80
	v_mul_f32_e32 v80, v87, v85
	v_mul_f32_e32 v83, v83, v80
	v_lshl_add_u64 v[84:85], v[96:97], 0, v[112:113]
	v_cvt_pk_bf16_f32 v80, v88, v89
	v_cvt_pk_bf16_f32 v81, v90, v91
	v_cvt_pk_bf16_f32 v82, v92, v93
	v_cvt_pk_bf16_f32 v83, v86, v83
	global_store_dwordx4 v[84:85], v[80:83], off sc1
	s_nop 1
; __device__ __forceinline__ unsigned pkbf(float lo, float hi) { return pg8::cvt_pk_bf16(lo, hi); }
; __device__ __forceinline__ float fsigmoid(float x) { return __builtin_amdgcn_rcpf(1.f + __builtin_amdgcn_exp2f(-1.4426950408889634f * x)); }
;     __device__ __forceinline__ void operator()(AccRef acc, const Unit& u, int wr, int wc, int fr, int fq) const {
;         asm volatile("" : "+v"(fr), "+v"(fq));
;         const int row0 = u.pm * 256 + wr * 64 + fr, col0 = u.pn * 128 + wc * 32 + 8 * fq;
; #pragma unroll
;         for (int ai = 0; ai < 2; ++ai)
; #pragma unroll
;             for (int m = 0; m < 4; ++m) {
;                 bf16_t* rowp = O + (size_t)(row0 + ai * 128 + m * 16) * DFF + col0;
;                 float o[8];
; #pragma unroll
;                 for (int n = 0; n < 2; ++n)
; #pragma unroll
;                     for (int e = 0; e < 4; ++e) { const float g = acc[ai][0][m][n][e], up = acc[ai][1][m][n][e]; o[n * 4 + e] = g * fsigmoid(g) * up; }
;                 u32x4 w; w.x = pkbf(o[0], o[1]); w.y = pkbf(o[2], o[3]); w.z = pkbf(o[4], o[5]); w.w = pkbf(o[6], o[7]);
;                 *(u32x4*)rowp = w; __builtin_amdgcn_sched_barrier(0); asm volatile("" ::: "memory");
;             }
	v_mul_f32_e32 v80, 0xbfb8aa3b, v76
	v_exp_f32_e32 v80, v80
	v_mul_f32_e32 v81, 0xbfb8aa3b, v77
	v_exp_f32_e32 v81, v81
	v_add_u32_e32 v82, 48, v153
	v_add_f32_e32 v80, 1.0, v80
	v_rcp_f32_e32 v83, v80
	v_add_f32_e32 v80, 1.0, v81
	v_rcp_f32_e32 v84, v80
	v_mad_i64_i32 v[80:81], s[4:5], v82, s57, v[146:147]
	v_mul_f32_e32 v76, v76, v83
	v_mul_f32_e32 v72, v72, v76
	v_mul_f32_e32 v76, v77, v84
	v_mul_f32_e32 v77, 0xbfb8aa3b, v78
	v_exp_f32_e32 v77, v77
	v_mul_f32_e32 v82, 0xbfb8aa3b, v79
	v_exp_f32_e32 v82, v82
	v_mul_f32_e32 v73, v73, v76
	v_add_f32_e32 v76, 1.0, v77
	v_rcp_f32_e32 v76, v76
	v_add_f32_e32 v77, 1.0, v82
	v_mul_f32_e32 v82, 0xbfb8aa3b, v68
	v_rcp_f32_e32 v77, v77
	v_exp_f32_e32 v82, v82
	v_mul_f32_e32 v76, v78, v76
	v_mul_f32_e32 v74, v74, v76
	v_mul_f32_e32 v76, v79, v77
	v_add_f32_e32 v77, 1.0, v82
	v_rcp_f32_e32 v77, v77
	v_mul_f32_e32 v78, 0xbfb8aa3b, v69
	v_exp_f32_e32 v78, v78
	v_mul_f32_e32 v75, v75, v76
	v_mul_f32_e32 v68, v68, v77
	v_mul_f32_e32 v76, v64, v68
	v_mul_f32_e32 v68, 0xbfb8aa3b, v70
	v_add_f32_e32 v64, 1.0, v78
	v_exp_f32_e32 v68, v68
	v_mul_f32_e32 v77, 0xbfb8aa3b, v71
	v_rcp_f32_e32 v64, v64
	v_exp_f32_e32 v77, v77
	v_add_f32_e32 v68, 1.0, v68
	v_rcp_f32_e32 v68, v68
	v_mul_f32_e32 v64, v69, v64
	v_add_f32_e32 v69, 1.0, v77
	v_rcp_f32_e32 v69, v69
	v_mul_f32_e32 v77, v65, v64
	v_mul_f32_e32 v64, v70, v68
	v_mul_f32_e32 v70, v66, v64
	v_mul_f32_e32 v64, v71, v69
	v_mul_f32_e32 v67, v67, v64
	v_lshl_add_u64 v[68:69], v[80:81], 0, v[112:113]
	v_cvt_pk_bf16_f32 v64, v72, v73
	v_cvt_pk_bf16_f32 v65, v74, v75
	v_cvt_pk_bf16_f32 v66, v76, v77
	v_cvt_pk_bf16_f32 v67, v70, v67
	global_store_dwordx4 v[68:69], v[64:67], off sc1
	s_nop 1
	v_mul_f32_e32 v64, 0xbfb8aa3b, v60
	v_exp_f32_e32 v64, v64
	v_mul_f32_e32 v65, 0xbfb8aa3b, v61
	v_exp_f32_e32 v65, v65
	v_add_u32_e32 v66, 0x80, v153
	v_add_f32_e32 v64, 1.0, v64
	v_rcp_f32_e32 v67, v64
	v_add_f32_e32 v64, 1.0, v65
	v_rcp_f32_e32 v68, v64
	v_mad_i64_i32 v[64:65], s[4:5], v66, s57, v[146:147]
	v_mul_f32_e32 v60, v60, v67
	v_mul_f32_e32 v56, v56, v60
	v_mul_f32_e32 v60, v61, v68
	v_mul_f32_e32 v61, 0xbfb8aa3b, v62
	v_exp_f32_e32 v61, v61
	v_mul_f32_e32 v66, 0xbfb8aa3b, v63
	v_exp_f32_e32 v66, v66
	v_mul_f32_e32 v57, v57, v60
	v_add_f32_e32 v60, 1.0, v61
	v_rcp_f32_e32 v60, v60
	v_add_f32_e32 v61, 1.0, v66
	v_mul_f32_e32 v66, 0xbfb8aa3b, v52
	v_rcp_f32_e32 v61, v61
	v_exp_f32_e32 v66, v66
	v_mul_f32_e32 v60, v62, v60
	v_mul_f32_e32 v58, v58, v60
	v_mul_f32_e32 v60, v63, v61
	v_add_f32_e32 v61, 1.0, v66
	v_rcp_f32_e32 v61, v61
	v_mul_f32_e32 v62, 0xbfb8aa3b, v53
	v_exp_f32_e32 v62, v62
	v_mul_f32_e32 v59, v59, v60
	v_mul_f32_e32 v52, v52, v61
	v_mul_f32_e32 v60, v48, v52
	v_mul_f32_e32 v52, 0xbfb8aa3b, v54
	v_add_f32_e32 v48, 1.0, v62
	v_exp_f32_e32 v52, v52
	v_mul_f32_e32 v61, 0xbfb8aa3b, v55
	v_rcp_f32_e32 v48, v48
	v_exp_f32_e32 v61, v61
	v_add_f32_e32 v52, 1.0, v52
	v_rcp_f32_e32 v52, v52
	v_mul_f32_e32 v48, v53, v48
	v_add_f32_e32 v53, 1.0, v61
	v_rcp_f32_e32 v53, v53
	v_mul_f32_e32 v61, v49, v48
	v_mul_f32_e32 v48, v54, v52
	v_mul_f32_e32 v54, v50, v48
	v_mul_f32_e32 v48, v55, v53
	v_mul_f32_e32 v51, v51, v48
	v_lshl_add_u64 v[52:53], v[64:65], 0, v[112:113]
	v_cvt_pk_bf16_f32 v48, v56, v57
	v_cvt_pk_bf16_f32 v49, v58, v59
	v_cvt_pk_bf16_f32 v50, v60, v61
	v_cvt_pk_bf16_f32 v51, v54, v51
	global_store_dwordx4 v[52:53], v[48:51], off sc1
	s_nop 1
	v_mul_f32_e32 v48, 0xbfb8aa3b, v44
	v_exp_f32_e32 v48, v48
	v_mul_f32_e32 v49, 0xbfb8aa3b, v45
	v_exp_f32_e32 v49, v49
	v_add_u32_e32 v50, 0x90, v153
	v_add_f32_e32 v48, 1.0, v48
	v_rcp_f32_e32 v51, v48
	v_add_f32_e32 v48, 1.0, v49
	v_rcp_f32_e32 v52, v48
	v_mad_i64_i32 v[48:49], s[4:5], v50, s57, v[146:147]
	v_mul_f32_e32 v44, v44, v51
	v_mul_f32_e32 v40, v40, v44
	v_mul_f32_e32 v44, v45, v52
	v_mul_f32_e32 v45, 0xbfb8aa3b, v46
	v_exp_f32_e32 v45, v45
	v_mul_f32_e32 v50, 0xbfb8aa3b, v47
	v_exp_f32_e32 v50, v50
	v_mul_f32_e32 v41, v41, v44
	v_add_f32_e32 v44, 1.0, v45
	v_rcp_f32_e32 v44, v44
	v_add_f32_e32 v45, 1.0, v50
	v_mul_f32_e32 v50, 0xbfb8aa3b, v36
	v_rcp_f32_e32 v45, v45
	v_exp_f32_e32 v50, v50
	v_mul_f32_e32 v44, v46, v44
	v_mul_f32_e32 v42, v42, v44
	v_mul_f32_e32 v44, v47, v45
	v_add_f32_e32 v45, 1.0, v50
	v_rcp_f32_e32 v45, v45
	v_mul_f32_e32 v46, 0xbfb8aa3b, v37
; #define PG8_BAR __builtin_amdgcn_s_barrier()
; __device__ __forceinline__ unsigned pkbf(float lo, float hi) { return pg8::cvt_pk_bf16(lo, hi); }
; __device__ __forceinline__ float fsigmoid(float x) { return __builtin_amdgcn_rcpf(1.f + __builtin_amdgcn_exp2f(-1.4426950408889634f * x)); }
; template <class Epi, class Sched, bool ALIGN_EPI = false, bool SP2 = false>
; __device__ __forceinline__ void gemm_phase(PG8_LAS unsigned char* lds, const Gemm g, const Sched& S, const Epi& E) {
;     ...
;         if constexpr (ALIGN_EPI) { if (wr == 0) PG8_BAR; }
;         if constexpr (!Epi::AFTER_DRAIN) { E(acc, cur, wr, wc, fr, fq); S.done(cur); }
;         if (!has_next) break;
; #pragma unroll
;         for (int a = 0; a < 2; ++a)
; #pragma unroll
;             for (int b = 0; b < 2; ++b)
; #pragma unroll
;                 for (int m = 0; m < 4; ++m)
; #pragma unroll
;                     for (int n = 0; n < 2; ++n) acc[a][b][m][n] = (f32x4){0.f, 0.f, 0.f, 0.f};
;         cur = nxt; cA = nA; cB = nB; ++ui;
;         if constexpr (ALIGN_EPI) { if (wr == 1) PG8_BAR; }
;     }
;     __device__ __forceinline__ void operator()(AccRef acc, const Unit& u, int wr, int wc, int fr, int fq) const {
;         asm volatile("" : "+v"(fr), "+v"(fq));
;         const int row0 = u.pm * 256 + wr * 64 + fr, col0 = u.pn * 128 + wc * 32 + 8 * fq;
; #pragma unroll
;         for (int ai = 0; ai < 2; ++ai)
; #pragma unroll
;             for (int m = 0; m < 4; ++m) {
;                 bf16_t* rowp = O + (size_t)(row0 + ai * 128 + m * 16) * DFF + col0;
;                 float o[8];
; #pragma unroll
;                 for (int n = 0; n < 2; ++n)
; #pragma unroll
;                     for (int e = 0; e < 4; ++e) { const float g = acc[ai][0][m][n][e], up = acc[ai][1][m][n][e]; o[n * 4 + e] = g * fsigmoid(g) * up; }
;                 u32x4 w; w.x = pkbf(o[0], o[1]); w.y = pkbf(o[2], o[3]); w.z = pkbf(o[4], o[5]); w.w = pkbf(o[6], o[7]);
;                 *(u32x4*)rowp = w; __builtin_amdgcn_sched_barrier(0); asm volatile("" ::: "memory");
;             }
;     }
	v_exp_f32_e32 v46, v46
	v_mul_f32_e32 v43, v43, v44
	v_mul_f32_e32 v36, v36, v45
	v_mul_f32_e32 v44, v32, v36
	v_mul_f32_e32 v36, 0xbfb8aa3b, v38
	v_add_f32_e32 v32, 1.0, v46
	v_exp_f32_e32 v36, v36
	v_mul_f32_e32 v45, 0xbfb8aa3b, v39
	v_rcp_f32_e32 v32, v32
	v_exp_f32_e32 v45, v45
	v_add_f32_e32 v36, 1.0, v36
	v_rcp_f32_e32 v36, v36
	v_mul_f32_e32 v32, v37, v32
	v_add_f32_e32 v37, 1.0, v45
	v_rcp_f32_e32 v37, v37
	v_mul_f32_e32 v45, v33, v32
	v_mul_f32_e32 v32, v38, v36
	v_mul_f32_e32 v38, v34, v32
	v_mul_f32_e32 v32, v39, v37
	v_mul_f32_e32 v35, v35, v32
	v_lshl_add_u64 v[36:37], v[48:49], 0, v[112:113]
	v_cvt_pk_bf16_f32 v32, v40, v41
	v_cvt_pk_bf16_f32 v33, v42, v43
	v_cvt_pk_bf16_f32 v34, v44, v45
	v_cvt_pk_bf16_f32 v35, v38, v35
	global_store_dwordx4 v[36:37], v[32:35], off sc1
	s_nop 1
	v_mul_f32_e32 v32, 0xbfb8aa3b, v28
	v_exp_f32_e32 v32, v32
	v_mul_f32_e32 v33, 0xbfb8aa3b, v29
	v_exp_f32_e32 v33, v33
	v_add_u32_e32 v34, 0xa0, v153
	v_add_f32_e32 v32, 1.0, v32
	v_rcp_f32_e32 v35, v32
	v_add_f32_e32 v32, 1.0, v33
	v_rcp_f32_e32 v36, v32
	v_mad_i64_i32 v[32:33], s[4:5], v34, s57, v[146:147]
	v_mul_f32_e32 v28, v28, v35
	v_mul_f32_e32 v24, v24, v28
	v_mul_f32_e32 v28, v29, v36
	v_mul_f32_e32 v29, 0xbfb8aa3b, v30
	v_exp_f32_e32 v29, v29
	v_mul_f32_e32 v34, 0xbfb8aa3b, v31
	v_exp_f32_e32 v34, v34
	v_mul_f32_e32 v25, v25, v28
	v_add_f32_e32 v28, 1.0, v29
	v_rcp_f32_e32 v28, v28
	v_add_f32_e32 v29, 1.0, v34
	v_mul_f32_e32 v34, 0xbfb8aa3b, v20
	v_rcp_f32_e32 v29, v29
	v_exp_f32_e32 v34, v34
	v_mul_f32_e32 v28, v30, v28
	v_mul_f32_e32 v26, v26, v28
	v_mul_f32_e32 v28, v31, v29
	v_add_f32_e32 v29, 1.0, v34
	v_rcp_f32_e32 v29, v29
	v_mul_f32_e32 v30, 0xbfb8aa3b, v21
	v_exp_f32_e32 v30, v30
	v_mul_f32_e32 v27, v27, v28
	v_mul_f32_e32 v20, v20, v29
	v_mul_f32_e32 v28, v16, v20
	v_mul_f32_e32 v20, 0xbfb8aa3b, v22
	v_add_f32_e32 v16, 1.0, v30
	v_exp_f32_e32 v20, v20
	v_mul_f32_e32 v29, 0xbfb8aa3b, v23
	v_rcp_f32_e32 v16, v16
	v_exp_f32_e32 v29, v29
	v_add_f32_e32 v20, 1.0, v20
	v_rcp_f32_e32 v20, v20
	v_mul_f32_e32 v16, v21, v16
	v_add_f32_e32 v21, 1.0, v29
	v_rcp_f32_e32 v21, v21
	v_mul_f32_e32 v29, v17, v16
	v_mul_f32_e32 v16, v22, v20
	v_mul_f32_e32 v22, v18, v16
	v_mul_f32_e32 v16, v23, v21
	v_mul_f32_e32 v19, v19, v16
	v_lshl_add_u64 v[20:21], v[32:33], 0, v[112:113]
	v_cvt_pk_bf16_f32 v16, v24, v25
	v_cvt_pk_bf16_f32 v17, v26, v27
	v_cvt_pk_bf16_f32 v18, v28, v29
	v_cvt_pk_bf16_f32 v19, v22, v19
	global_store_dwordx4 v[20:21], v[16:19], off sc1
	s_nop 1
	v_mul_f32_e32 v16, 0xbfb8aa3b, v12
	v_exp_f32_e32 v16, v16
	v_mul_f32_e32 v17, 0xbfb8aa3b, v13
	v_exp_f32_e32 v17, v17
	v_add_u32_e32 v18, 0xb0, v153
	v_add_f32_e32 v16, 1.0, v16
	v_rcp_f32_e32 v19, v16
	v_add_f32_e32 v16, 1.0, v17
	v_rcp_f32_e32 v20, v16
	v_mad_i64_i32 v[16:17], s[4:5], v18, s57, v[146:147]
	v_mul_f32_e32 v12, v12, v19
	v_mul_f32_e32 v8, v8, v12
	v_mul_f32_e32 v12, v13, v20
	v_mul_f32_e32 v13, 0xbfb8aa3b, v14
	v_exp_f32_e32 v13, v13
	v_mul_f32_e32 v18, 0xbfb8aa3b, v15
	v_exp_f32_e32 v18, v18
	v_mul_f32_e32 v9, v9, v12
	v_add_f32_e32 v12, 1.0, v13
	v_rcp_f32_e32 v12, v12
	v_add_f32_e32 v13, 1.0, v18
	v_mul_f32_e32 v18, 0xbfb8aa3b, v4
	v_rcp_f32_e32 v13, v13
	v_exp_f32_e32 v18, v18
	v_mul_f32_e32 v12, v14, v12
	v_mul_f32_e32 v10, v10, v12
	v_mul_f32_e32 v12, v15, v13
	v_add_f32_e32 v13, 1.0, v18
	v_rcp_f32_e32 v13, v13
	v_mul_f32_e32 v14, 0xbfb8aa3b, v5
	v_exp_f32_e32 v14, v14
	v_mul_f32_e32 v11, v11, v12
	v_mul_f32_e32 v4, v4, v13
	v_mul_f32_e32 v12, v0, v4
	v_mul_f32_e32 v4, 0xbfb8aa3b, v6
	v_add_f32_e32 v0, 1.0, v14
	v_exp_f32_e32 v4, v4
	v_mul_f32_e32 v13, 0xbfb8aa3b, v7
	v_rcp_f32_e32 v0, v0
	v_exp_f32_e32 v13, v13
	v_add_f32_e32 v4, 1.0, v4
	v_rcp_f32_e32 v4, v4
	v_mul_f32_e32 v0, v5, v0
	v_add_f32_e32 v5, 1.0, v13
	v_rcp_f32_e32 v5, v5
	v_mul_f32_e32 v13, v1, v0
	v_mul_f32_e32 v0, v6, v4
	v_mul_f32_e32 v6, v2, v0
	v_mul_f32_e32 v0, v7, v5
	v_mul_f32_e32 v3, v3, v0
	v_lshl_add_u64 v[4:5], v[16:17], 0, v[112:113]
	v_cvt_pk_bf16_f32 v0, v8, v9
	v_cvt_pk_bf16_f32 v1, v10, v11
	v_cvt_pk_bf16_f32 v2, v12, v13
	v_cvt_pk_bf16_f32 v3, v6, v3
	global_store_dwordx4 v[4:5], v[0:3], off sc1
	s_and_b64 vcc, exec, s[8:9]
	s_mov_b64 s[4:5], -1
	s_cbranch_vccnz .LBB0_1360
	s_andn2_b64 vcc, exec, s[16:17]
	s_cbranch_vccnz .LBB0_1359
	s_barrier
	s_branch .LBB0_1359
